# k15: remaining 66 IEEE division expansions (silu gate in P3b group-norm phase, tanh in P1s) replaced by v_rcp_f32 + v_mul_f32
# speedup vs baseline: 1.0063x; 1.0063x over previous
.LBB0_258:
	s_and_b32 s0, s18, 0x1fff
	s_cmp_eq_u32 s0, 0
	s_cselect_b64 vcc, -1, 0
	s_and_b64 s[0:1], vcc, exec
	v_lshl_add_u64 v[6:7], s[8:9], 0, v[0:1]
	s_cselect_b32 s1, 0, -1
	s_cselect_b32 s0, 0, 0xfffffe00
	global_load_dword v8, v[6:7], off
	v_lshl_add_u64 v[6:7], s[8:9], 0, v[4:5]
	v_lshl_add_u64 v[6:7], v[6:7], 0, s[0:1]
	global_load_dword v10, v[6:7], off
	s_waitcnt vmcnt(1)
	v_lshlrev_b32_e32 v7, 16, v8
	v_and_b32_e32 v6, 0xffff0000, v8
	s_waitcnt vmcnt(0)
	v_lshlrev_b32_e32 v9, 16, v10
	v_and_b32_e32 v8, 0xffff0000, v10
	v_pk_add_f32 v[8:9], v[6:7], v[8:9]
	s_nop 0
	v_cndmask_b32_e32 v7, v9, v7, vcc
	v_cndmask_b32_e32 v6, v8, v6, vcc
	s_and_saveexec_b64 s[0:1], s[6:7]
	s_cbranch_execz .LBB0_257
	v_add_f32_e32 v7, v7, v7
	v_add_f32_e32 v6, v6, v6
	v_mul_f32_e32 v7, 0x3fb8aa3b, v7
	v_mul_f32_e32 v6, 0x3fb8aa3b, v6
	v_exp_f32_e32 v7, v7
	v_exp_f32_e32 v6, v6
	s_nop 0
	v_pk_add_f32 v[6:7], v[6:7], 1.0 op_sel_hi:[1,0]
	s_nop 0
	v_rcp_f32_e32 v8, v7
	s_nop 0
	v_mul_f32_e32 v7, -2.0, v8
	v_rcp_f32_e32 v8, v6
	s_nop 0
	v_mul_f32_e32 v6, -2.0, v8
	v_pk_add_f32 v[6:7], v[6:7], 1.0 op_sel_hi:[1,0]
	s_branch .LBB0_257

.LBB0_904:
	v_lshl_add_u64 v[100:101], s[6:7], 0, v[92:93]
	v_add_co_u32_e32 v0, vcc, 0x27d00000, v100
	s_addk_i32 s0, 0xfc00
	s_nop 0
	v_addc_co_u32_e32 v1, vcc, 0, v101, vcc
	global_load_dwordx4 v[118:121], v[0:1], off
	global_load_dwordx4 v[80:83], v[0:1], off offset:1024
	v_lshl_add_u64 v[0:1], s[8:9], 0, v[92:93]
	v_add_co_u32_e32 v2, vcc, 0x8000000, v0
	s_add_u32 s6, s6, 0xffe00000
	s_nop 0
	v_addc_co_u32_e32 v3, vcc, 0, v1, vcc
	global_load_dwordx4 v[88:91], v[2:3], off
	global_load_dwordx4 v[76:79], v[2:3], off offset:1024
	v_add_co_u32_e32 v2, vcc, 0x7900000, v100
	s_addc_u32 s7, s7, -1
	s_nop 0
	v_addc_co_u32_e32 v3, vcc, 0, v101, vcc
	global_load_dwordx4 v[84:87], v[2:3], off
	global_load_dwordx4 v[72:75], v[2:3], off offset:1024
	global_load_dword v116, v[98:99], off
	global_load_dword v114, v[98:99], off offset:32
	v_add_co_u32_e32 v2, vcc, 0x27d80000, v100
	s_add_u32 s8, s8, 0xffe00000
	s_nop 0
	v_addc_co_u32_e32 v3, vcc, 0, v101, vcc
	global_load_dwordx4 v[68:71], v[2:3], off
	global_load_dwordx4 v[56:59], v[2:3], off offset:1024
	v_add_co_u32_e32 v2, vcc, 0x8080000, v0
	s_addc_u32 s9, s9, -1
	s_nop 0
	v_addc_co_u32_e32 v3, vcc, 0, v1, vcc
	global_load_dwordx4 v[64:67], v[2:3], off
	global_load_dwordx4 v[52:55], v[2:3], off offset:1024
	v_add_co_u32_e32 v2, vcc, 0x7980000, v100
	s_cmp_lt_i32 s0, s73
	s_nop 0
	v_addc_co_u32_e32 v3, vcc, 0, v101, vcc
	global_load_dwordx4 v[60:63], v[2:3], off
	global_load_dwordx4 v[48:51], v[2:3], off offset:1024
	v_add_co_u32_e32 v2, vcc, 0x4000, v98
	s_waitcnt vmcnt(13)
	v_and_b32_e32 v127, 0xffff0000, v120
	v_addc_co_u32_e32 v3, vcc, 0, v99, vcc
	global_load_dword v112, v[2:3], off
	global_load_dword v110, v[2:3], off offset:32
	v_add_co_u32_e32 v2, vcc, 0x27e00000, v100
	v_and_b32_e32 v126, 0xffff0000, v118
	s_nop 0
	v_addc_co_u32_e32 v3, vcc, 0, v101, vcc
	global_load_dwordx4 v[44:47], v[2:3], off
	global_load_dwordx4 v[32:35], v[2:3], off offset:1024
	v_add_co_u32_e32 v2, vcc, 0x8100000, v0
	v_lshlrev_b32_e32 v129, 16, v121
	s_nop 0
	v_addc_co_u32_e32 v3, vcc, 0, v1, vcc
	global_load_dwordx4 v[40:43], v[2:3], off
	global_load_dwordx4 v[28:31], v[2:3], off offset:1024
	v_add_co_u32_e32 v2, vcc, 0x7a00000, v100
	v_lshlrev_b32_e32 v128, 16, v119
	s_nop 0
	v_addc_co_u32_e32 v3, vcc, 0, v101, vcc
	global_load_dwordx4 v[36:39], v[2:3], off
	global_load_dwordx4 v[24:27], v[2:3], off offset:1024
	v_add_co_u32_e32 v2, vcc, 0x8000, v98
	v_and_b32_e32 v131, 0xffff0000, v121
	s_nop 0
	v_addc_co_u32_e32 v3, vcc, 0, v99, vcc
	global_load_dword v108, v[2:3], off
	global_load_dword v106, v[2:3], off offset:32
	v_add_co_u32_e32 v2, vcc, 0x27e80000, v100
	v_and_b32_e32 v130, 0xffff0000, v119
	s_nop 0
	v_addc_co_u32_e32 v3, vcc, 0, v101, vcc
	v_add_co_u32_e32 v0, vcc, 0x8180000, v0
	global_load_dwordx4 v[20:23], v[2:3], off
	global_load_dwordx4 v[8:11], v[2:3], off offset:1024
	v_addc_co_u32_e32 v1, vcc, 0, v1, vcc
	global_load_dwordx4 v[16:19], v[0:1], off
	global_load_dwordx4 v[4:7], v[0:1], off offset:1024
	v_add_co_u32_e32 v0, vcc, 0x7a80000, v100
	s_waitcnt vmcnt(25)
	v_lshlrev_b32_e32 v144, 16, v88
	v_addc_co_u32_e32 v1, vcc, 0, v101, vcc
	v_add_co_u32_e32 v122, vcc, 0xc000, v98
	global_load_dwordx4 v[12:15], v[0:1], off
	s_nop 0
	global_load_dwordx4 v[0:3], v[0:1], off offset:1024
	v_addc_co_u32_e32 v123, vcc, 0, v99, vcc
	global_load_dword v104, v[122:123], off
	global_load_dword v102, v[122:123], off offset:32
	v_lshlrev_b32_e32 v123, 16, v120
	v_lshlrev_b32_e32 v122, 16, v118
	v_pk_add_f32 v[118:119], v[122:123], v[126:127]
	v_pk_add_f32 v[120:121], v[128:129], v[130:131]
	v_and_b32_e32 v145, 0xffff0000, v88
	v_pk_add_f32 v[118:119], v[118:119], v[120:121]
	v_lshlrev_b32_e32 v88, 16, v89
	v_add_f32_e32 v105, v118, v119
	v_and_b32_e32 v89, 0xffff0000, v89
	s_waitcnt vmcnt(27)
	v_and_b32_e32 v107, 0xffff0000, v84
	v_add_f32_dpp v105, v105, v105 quad_perm:[1,0,3,2] row_mask:0xf bank_mask:0xf bound_ctrl:1
	v_lshlrev_b32_e32 v109, 16, v85
	v_and_b32_e32 v111, 0xffff0000, v85
	v_add_f32_dpp v105, v105, v105 quad_perm:[2,3,0,1] row_mask:0xf bank_mask:0xf bound_ctrl:1
	v_mul_f32_e32 v85, 0xbfb8aa3b, v111
	v_exp_f32_e32 v85, v85
	v_add_f32_dpp v105, v105, v105 row_half_mirror row_mask:0xf bank_mask:0xf bound_ctrl:1
	v_fmac_f32_e32 v126, 0xbc800000, v105
	v_fmac_f32_e32 v127, 0xbc800000, v105
	v_fmac_f32_e32 v130, 0xbc800000, v105
	v_fmac_f32_e32 v122, 0xbc800000, v105
	v_fmac_f32_e32 v131, 0xbc800000, v105
	v_fmac_f32_e32 v123, 0xbc800000, v105
	v_pk_mul_f32 v[120:121], v[126:127], v[126:127]
	v_fmac_f32_e32 v128, 0xbc800000, v105
	v_fmac_f32_e32 v129, 0xbc800000, v105
	v_mov_b32_e32 v118, v123
	v_mov_b32_e32 v119, v127
	v_mov_b32_e32 v124, v122
	v_pk_fma_f32 v[122:123], v[122:123], v[122:123], v[120:121]
	v_mov_b32_e32 v121, v131
	v_mov_b32_e32 v127, v130
	v_pk_mul_f32 v[130:131], v[130:131], v[130:131]
	v_mov_b32_e32 v125, v126
	v_mov_b32_e32 v120, v129
	v_mov_b32_e32 v126, v128
	v_pk_fma_f32 v[128:129], v[128:129], v[128:129], v[130:131]
	v_lshl_add_u64 v[98:99], v[98:99], 0, s[10:11]
	v_pk_add_f32 v[122:123], v[122:123], v[128:129]
	global_load_dwordx4 v[128:131], v[94:95], off offset:16
	global_load_dwordx4 v[132:135], v[94:95], off
	global_load_dwordx4 v[136:139], v[96:97], off offset:16
	global_load_dwordx4 v[140:143], v[96:97], off
	v_add_f32_e32 v105, v122, v123
	s_nop 1
	v_add_f32_dpp v105, v105, v105 quad_perm:[1,0,3,2] row_mask:0xf bank_mask:0xf bound_ctrl:1
	s_nop 1
	v_add_f32_dpp v105, v105, v105 quad_perm:[2,3,0,1] row_mask:0xf bank_mask:0xf bound_ctrl:1
	s_nop 1
	v_add_f32_dpp v105, v105, v105 row_half_mirror row_mask:0xf bank_mask:0xf bound_ctrl:1
	v_fmamk_f32 v105, v105, 0x3c800000, v103
	v_rsq_f32_e32 v122, v105
	v_lshlrev_b32_e32 v105, 16, v84
	v_mul_f32_e32 v84, 0xbfb8aa3b, v105
	v_pk_mul_f32 v[126:127], v[122:123], v[126:127] op_sel_hi:[0,1]
	v_pk_mul_f32 v[124:125], v[122:123], v[124:125] op_sel_hi:[0,1]
	s_waitcnt vmcnt(0)
	v_pk_fma_f32 v[126:127], v[126:127], v[134:135], v[142:143]
	s_nop 0
	v_pk_fma_f32 v[88:89], v[116:117], v[88:89], v[126:127] op_sel_hi:[0,1,1]
	v_exp_f32_e32 v126, v84
	v_mul_f32_e32 v84, 0xbfb8aa3b, v107
	v_exp_f32_e32 v127, v84
	v_mul_f32_e32 v84, 0xbfb8aa3b, v109
	v_exp_f32_e32 v84, v84
	v_pk_fma_f32 v[124:125], v[124:125], v[132:133], v[140:141]
	v_pk_add_f32 v[126:127], v[126:127], 1.0 op_sel_hi:[1,0]
	v_pk_fma_f32 v[124:125], v[116:117], v[144:145], v[124:125] op_sel_hi:[0,1,1]
	v_pk_add_f32 v[84:85], v[84:85], 1.0 op_sel_hi:[1,0]
	s_nop 0
	v_rcp_f32_e32 v113, v85
	s_nop 0
	v_mul_f32_e32 v85, v111, v113
	v_rcp_f32_e32 v111, v84
	s_nop 0
	v_mul_f32_e32 v84, v109, v111
	v_pk_mul_f32 v[118:119], v[122:123], v[118:119] op_sel_hi:[0,1]
	v_pk_mul_f32 v[120:121], v[122:123], v[120:121] op_sel_hi:[0,1]
	v_pk_mul_f32 v[84:85], v[88:89], v[84:85]
	v_rcp_f32_e32 v109, v127
	s_nop 0
	v_mul_f32_e32 v127, v107, v109
	v_pk_fma_f32 v[120:121], v[120:121], v[130:131], v[138:139]
	v_pk_fma_f32 v[118:119], v[118:119], v[128:129], v[136:137]
	v_lshlrev_b32_e32 v123, 16, v83
	v_rcp_f32_e32 v107, v126
	s_nop 0
	v_mul_f32_e32 v126, v105, v107
	v_lshlrev_b32_e32 v105, 16, v86
	v_pk_mul_f32 v[88:89], v[124:125], v[126:127]
	v_lshlrev_b32_e32 v124, 16, v90
	v_and_b32_e32 v125, 0xffff0000, v90
	v_lshlrev_b32_e32 v90, 16, v91
	v_and_b32_e32 v91, 0xffff0000, v91
	v_and_b32_e32 v107, 0xffff0000, v86
	v_mul_f32_e32 v86, 0xbfb8aa3b, v105
	v_pk_fma_f32 v[118:119], v[116:117], v[124:125], v[118:119] op_sel_hi:[0,1,1]
	v_pk_fma_f32 v[90:91], v[116:117], v[90:91], v[120:121] op_sel_hi:[0,1,1]
	v_exp_f32_e32 v116, v86
	v_mul_f32_e32 v86, 0xbfb8aa3b, v107
	v_lshlrev_b32_e32 v109, 16, v87
	v_and_b32_e32 v111, 0xffff0000, v87
	v_exp_f32_e32 v117, v86
	v_mul_f32_e32 v86, 0xbfb8aa3b, v109
	v_mul_f32_e32 v87, 0xbfb8aa3b, v111
	v_exp_f32_e32 v86, v86
	v_exp_f32_e32 v87, v87
	v_pk_add_f32 v[116:117], v[116:117], 1.0 op_sel_hi:[1,0]
	v_and_b32_e32 v125, 0xffff0000, v83
	v_and_b32_e32 v124, 0xffff0000, v81
	v_pk_add_f32 v[86:87], v[86:87], 1.0 op_sel_hi:[1,0]
	v_lshlrev_b32_e32 v138, 16, v76
	v_and_b32_e32 v139, 0xffff0000, v76
	v_lshlrev_b32_e32 v76, 16, v77
	v_and_b32_e32 v77, 0xffff0000, v77
	v_rcp_f32_e32 v113, v87
	s_nop 0
	v_mul_f32_e32 v87, v111, v113
	v_lshlrev_b32_e32 v122, 16, v81
	v_rcp_f32_e32 v111, v86
	s_nop 0
	v_mul_f32_e32 v86, v109, v111
	v_pk_mul_f32 v[86:87], v[90:91], v[86:87]
	v_and_b32_e32 v121, 0xffff0000, v82
	v_rcp_f32_e32 v109, v117
	s_nop 0
	v_mul_f32_e32 v117, v107, v109
	v_and_b32_e32 v120, 0xffff0000, v80
	v_rcp_f32_e32 v107, v116
	s_nop 0
	v_mul_f32_e32 v116, v105, v107
	v_pk_mul_f32 v[90:91], v[118:119], v[116:117]
	v_lshlrev_b32_e32 v117, 16, v82
	v_lshlrev_b32_e32 v116, 16, v80
	v_pk_add_f32 v[80:81], v[116:117], v[120:121]
	v_pk_add_f32 v[82:83], v[122:123], v[124:125]
	v_and_b32_e32 v107, 0xffff0000, v72
	v_pk_add_f32 v[80:81], v[80:81], v[82:83]
	v_lshlrev_b32_e32 v109, 16, v73
	v_add_f32_e32 v80, v80, v81
	v_and_b32_e32 v111, 0xffff0000, v73
	v_mul_f32_e32 v73, 0xbfb8aa3b, v111
	v_add_f32_dpp v80, v80, v80 quad_perm:[1,0,3,2] row_mask:0xf bank_mask:0xf bound_ctrl:1
	v_exp_f32_e32 v73, v73
	s_nop 0
	v_add_f32_dpp v80, v80, v80 quad_perm:[2,3,0,1] row_mask:0xf bank_mask:0xf bound_ctrl:1
	s_nop 1
	v_add_f32_dpp v80, v80, v80 row_half_mirror row_mask:0xf bank_mask:0xf bound_ctrl:1
	v_fmac_f32_e32 v120, 0xbc800000, v80
	v_fmac_f32_e32 v121, 0xbc800000, v80
	v_fmac_f32_e32 v124, 0xbc800000, v80
	v_fmac_f32_e32 v116, 0xbc800000, v80
	v_fmac_f32_e32 v125, 0xbc800000, v80
	v_fmac_f32_e32 v117, 0xbc800000, v80
	v_pk_mul_f32 v[82:83], v[120:121], v[120:121]
	v_fmac_f32_e32 v122, 0xbc800000, v80
	v_fmac_f32_e32 v123, 0xbc800000, v80
	v_mov_b32_e32 v80, v117
	v_mov_b32_e32 v81, v121
	v_mov_b32_e32 v118, v116
	v_pk_fma_f32 v[116:117], v[116:117], v[116:117], v[82:83]
	v_mov_b32_e32 v83, v125
	v_mov_b32_e32 v121, v124
	v_pk_mul_f32 v[124:125], v[124:125], v[124:125]
	v_mov_b32_e32 v119, v120
	v_mov_b32_e32 v82, v123
	v_mov_b32_e32 v120, v122
	v_pk_fma_f32 v[122:123], v[122:123], v[122:123], v[124:125]
	s_nop 0
	v_pk_add_f32 v[116:117], v[116:117], v[122:123]
	global_load_dwordx4 v[122:125], v[94:95], off offset:2064
	global_load_dwordx4 v[126:129], v[94:95], off offset:2048
	global_load_dwordx4 v[130:133], v[96:97], off offset:2064
	global_load_dwordx4 v[134:137], v[96:97], off offset:2048
	v_add_f32_e32 v105, v116, v117
	s_nop 1
	v_add_f32_dpp v105, v105, v105 quad_perm:[1,0,3,2] row_mask:0xf bank_mask:0xf bound_ctrl:1
	s_nop 1
	v_add_f32_dpp v105, v105, v105 quad_perm:[2,3,0,1] row_mask:0xf bank_mask:0xf bound_ctrl:1
	s_nop 1
	v_add_f32_dpp v105, v105, v105 row_half_mirror row_mask:0xf bank_mask:0xf bound_ctrl:1
	v_fmamk_f32 v105, v105, 0x3c800000, v103
	v_rsq_f32_e32 v116, v105
	v_lshlrev_b32_e32 v105, 16, v72
	v_mul_f32_e32 v72, 0xbfb8aa3b, v105
	v_pk_mul_f32 v[120:121], v[116:117], v[120:121] op_sel_hi:[0,1]
	v_pk_mul_f32 v[118:119], v[116:117], v[118:119] op_sel_hi:[0,1]
	s_waitcnt vmcnt(0)
	v_pk_fma_f32 v[120:121], v[120:121], v[128:129], v[136:137]
	s_nop 0
	v_pk_fma_f32 v[76:77], v[114:115], v[76:77], v[120:121] op_sel_hi:[0,1,1]
	v_exp_f32_e32 v120, v72
	v_mul_f32_e32 v72, 0xbfb8aa3b, v107
	v_exp_f32_e32 v121, v72
	v_mul_f32_e32 v72, 0xbfb8aa3b, v109
	v_exp_f32_e32 v72, v72
	v_pk_fma_f32 v[118:119], v[118:119], v[126:127], v[134:135]
	v_pk_add_f32 v[120:121], v[120:121], 1.0 op_sel_hi:[1,0]
	v_pk_fma_f32 v[118:119], v[114:115], v[138:139], v[118:119] op_sel_hi:[0,1,1]
	v_pk_add_f32 v[72:73], v[72:73], 1.0 op_sel_hi:[1,0]
	s_nop 0
	v_rcp_f32_e32 v113, v73
	s_nop 0
	v_mul_f32_e32 v73, v111, v113
	v_rcp_f32_e32 v111, v72
	s_nop 0
	v_mul_f32_e32 v72, v109, v111
	v_pk_mul_f32 v[76:77], v[76:77], v[72:73]
	v_lshlrev_b32_e32 v72, 16, v78
	v_and_b32_e32 v73, 0xffff0000, v78
	v_rcp_f32_e32 v109, v121
	s_nop 0
	v_mul_f32_e32 v121, v107, v109
	v_pk_mul_f32 v[82:83], v[116:117], v[82:83] op_sel_hi:[0,1]
	v_lshlrev_b32_e32 v78, 16, v79
	v_and_b32_e32 v79, 0xffff0000, v79
	v_pk_fma_f32 v[82:83], v[82:83], v[124:125], v[132:133]
	v_pk_mul_f32 v[80:81], v[116:117], v[80:81] op_sel_hi:[0,1]
	v_pk_fma_f32 v[78:79], v[114:115], v[78:79], v[82:83] op_sel_hi:[0,1,1]
	v_lshlrev_b32_e32 v82, 16, v74
	v_pk_fma_f32 v[80:81], v[80:81], v[122:123], v[130:131]
	v_and_b32_e32 v83, 0xffff0000, v74
	v_mul_f32_e32 v74, 0xbfb8aa3b, v82
	v_rcp_f32_e32 v107, v120
	s_nop 0
	v_mul_f32_e32 v120, v105, v107
	v_pk_fma_f32 v[72:73], v[114:115], v[72:73], v[80:81] op_sel_hi:[0,1,1]
	v_exp_f32_e32 v80, v74
	v_mul_f32_e32 v74, 0xbfb8aa3b, v83
	v_lshlrev_b32_e32 v105, 16, v75
	v_and_b32_e32 v107, 0xffff0000, v75
	v_exp_f32_e32 v81, v74
	v_mul_f32_e32 v74, 0xbfb8aa3b, v105
	v_mul_f32_e32 v75, 0xbfb8aa3b, v107
	v_exp_f32_e32 v74, v74
	v_exp_f32_e32 v75, v75
	v_pk_add_f32 v[80:81], v[80:81], 1.0 op_sel_hi:[1,0]
	v_pk_mul_f32 v[118:119], v[118:119], v[120:121]
	v_lshlrev_b32_e32 v116, 16, v64
	v_pk_add_f32 v[74:75], v[74:75], 1.0 op_sel_hi:[1,0]
	v_and_b32_e32 v117, 0xffff0000, v64
	v_lshlrev_b32_e32 v64, 16, v65
	v_and_b32_e32 v65, 0xffff0000, v65
	v_rcp_f32_e32 v109, v75
	s_nop 0
	v_mul_f32_e32 v75, v107, v109
	v_rcp_f32_e32 v107, v74
	s_nop 0
	v_mul_f32_e32 v74, v105, v107
	v_pk_mul_f32 v[78:79], v[78:79], v[74:75]
	v_rcp_f32_e32 v105, v81
	s_nop 0
	v_mul_f32_e32 v81, v83, v105
	v_rcp_f32_e32 v83, v80
	s_nop 0
	v_mul_f32_e32 v80, v82, v83
	v_add_co_u32_e32 v82, vcc, s1, v100
	v_pk_mul_f32 v[80:81], v[72:73], v[80:81]
	v_cvt_pk_bf16_f32 v72, v88, v89
	v_cvt_pk_bf16_f32 v73, v84, v85
	v_cvt_pk_bf16_f32 v74, v90, v91
	v_cvt_pk_bf16_f32 v75, v86, v87
	s_nop 0
	v_addc_co_u32_e32 v83, vcc, 0, v101, vcc
	global_store_dwordx4 v[82:83], v[72:75], off
	s_nop 1
	v_cvt_pk_bf16_f32 v72, v118, v119
	v_cvt_pk_bf16_f32 v73, v76, v77
	v_cvt_pk_bf16_f32 v74, v80, v81
	v_cvt_pk_bf16_f32 v75, v78, v79
	global_store_dwordx4 v[82:83], v[72:75], off offset:1024
	v_lshlrev_b32_e32 v77, 16, v71
	v_lshlrev_b32_e32 v76, 16, v69
	v_lshlrev_b32_e32 v73, 16, v70
	v_lshlrev_b32_e32 v72, 16, v68
	v_and_b32_e32 v75, 0xffff0000, v70
	v_and_b32_e32 v74, 0xffff0000, v68
	v_and_b32_e32 v71, 0xffff0000, v71
	v_and_b32_e32 v70, 0xffff0000, v69
	v_pk_add_f32 v[68:69], v[72:73], v[74:75]
	v_pk_add_f32 v[78:79], v[76:77], v[70:71]
	s_nop 0
	v_pk_add_f32 v[68:69], v[68:69], v[78:79]
	s_nop 0
	v_add_f32_e32 v68, v68, v69
	s_nop 1
	v_add_f32_dpp v68, v68, v68 quad_perm:[1,0,3,2] row_mask:0xf bank_mask:0xf bound_ctrl:1
	s_nop 1
	v_add_f32_dpp v68, v68, v68 quad_perm:[2,3,0,1] row_mask:0xf bank_mask:0xf bound_ctrl:1
	s_nop 1
	v_add_f32_dpp v68, v68, v68 row_half_mirror row_mask:0xf bank_mask:0xf bound_ctrl:1
	v_fmac_f32_e32 v70, 0xbc800000, v68
	v_fmac_f32_e32 v74, 0xbc800000, v68
	v_fmac_f32_e32 v71, 0xbc800000, v68
	v_fmac_f32_e32 v75, 0xbc800000, v68
	v_fmac_f32_e32 v76, 0xbc800000, v68
	v_fmac_f32_e32 v72, 0xbc800000, v68
	v_fmac_f32_e32 v77, 0xbc800000, v68
	v_fmac_f32_e32 v73, 0xbc800000, v68
	v_pk_mul_f32 v[68:69], v[74:75], v[74:75]
	v_mov_b32_e32 v89, v71
	v_mov_b32_e32 v91, v70
	v_pk_mul_f32 v[70:71], v[70:71], v[70:71]
	v_pk_fma_f32 v[68:69], v[72:73], v[72:73], v[68:69]
	v_pk_fma_f32 v[70:71], v[76:77], v[76:77], v[70:71]
	v_mov_b32_e32 v84, v73
	v_pk_add_f32 v[68:69], v[68:69], v[70:71]
	v_mov_b32_e32 v85, v75
	v_add_f32_e32 v68, v68, v69
	v_mov_b32_e32 v86, v72
	v_mov_b32_e32 v87, v74
	v_add_f32_dpp v68, v68, v68 quad_perm:[1,0,3,2] row_mask:0xf bank_mask:0xf bound_ctrl:1
	v_mov_b32_e32 v88, v77
	v_mov_b32_e32 v90, v76
	v_add_f32_dpp v68, v68, v68 quad_perm:[2,3,0,1] row_mask:0xf bank_mask:0xf bound_ctrl:1
	s_nop 1
	v_add_f32_dpp v68, v68, v68 row_half_mirror row_mask:0xf bank_mask:0xf bound_ctrl:1
	v_fmamk_f32 v68, v68, 0x3c800000, v103
	v_rsq_f32_e32 v114, v68
	global_load_dwordx4 v[68:71], v[94:95], off offset:16
	global_load_dwordx4 v[72:75], v[94:95], off
	global_load_dwordx4 v[76:79], v[96:97], off offset:16
	global_load_dwordx4 v[80:83], v[96:97], off
	v_pk_mul_f32 v[86:87], v[114:115], v[86:87] op_sel_hi:[0,1]
	v_pk_mul_f32 v[90:91], v[114:115], v[90:91] op_sel_hi:[0,1]
	s_waitcnt vmcnt(0)
	v_pk_fma_f32 v[72:73], v[86:87], v[72:73], v[80:81]
	v_lshlrev_b32_e32 v80, 16, v60
	v_pk_fma_f32 v[74:75], v[90:91], v[74:75], v[82:83]
	v_and_b32_e32 v81, 0xffff0000, v60
	v_mul_f32_e32 v60, 0xbfb8aa3b, v80
	v_pk_fma_f32 v[64:65], v[112:113], v[64:65], v[74:75] op_sel_hi:[0,1,1]
	v_exp_f32_e32 v74, v60
	v_mul_f32_e32 v60, 0xbfb8aa3b, v81
	v_lshlrev_b32_e32 v82, 16, v61
	v_and_b32_e32 v83, 0xffff0000, v61
	v_exp_f32_e32 v75, v60
	v_mul_f32_e32 v60, 0xbfb8aa3b, v82
	v_mul_f32_e32 v61, 0xbfb8aa3b, v83
	v_exp_f32_e32 v60, v60
	v_exp_f32_e32 v61, v61
	v_pk_add_f32 v[74:75], v[74:75], 1.0 op_sel_hi:[1,0]
	v_pk_fma_f32 v[72:73], v[112:113], v[116:117], v[72:73] op_sel_hi:[0,1,1]
	v_pk_add_f32 v[60:61], v[60:61], 1.0 op_sel_hi:[1,0]
	s_nop 0
	v_rcp_f32_e32 v86, v61
	s_nop 0
	v_mul_f32_e32 v61, v83, v86
	v_rcp_f32_e32 v83, v60
	s_nop 0
	v_mul_f32_e32 v60, v82, v83
	v_pk_mul_f32 v[60:61], v[64:65], v[60:61]
	v_and_b32_e32 v91, 0xffff0000, v52
	v_rcp_f32_e32 v82, v75
	s_nop 0
	v_mul_f32_e32 v75, v81, v82
	v_lshlrev_b32_e32 v90, 16, v52
	v_lshlrev_b32_e32 v52, 16, v53
	v_and_b32_e32 v53, 0xffff0000, v53
	v_rcp_f32_e32 v81, v74
	s_nop 0
	v_mul_f32_e32 v74, v80, v81
	v_pk_mul_f32 v[64:65], v[72:73], v[74:75]
	v_pk_mul_f32 v[74:75], v[114:115], v[84:85] op_sel_hi:[0,1]
	v_lshlrev_b32_e32 v72, 16, v66
	v_and_b32_e32 v73, 0xffff0000, v66
	v_pk_fma_f32 v[68:69], v[74:75], v[68:69], v[76:77]
	v_pk_mul_f32 v[80:81], v[114:115], v[88:89] op_sel_hi:[0,1]
	v_pk_fma_f32 v[68:69], v[112:113], v[72:73], v[68:69] op_sel_hi:[0,1,1]
	v_lshlrev_b32_e32 v72, 16, v62
	v_lshlrev_b32_e32 v66, 16, v67
	v_and_b32_e32 v67, 0xffff0000, v67
	v_pk_fma_f32 v[70:71], v[80:81], v[70:71], v[78:79]
	v_and_b32_e32 v73, 0xffff0000, v62
	v_mul_f32_e32 v62, 0xbfb8aa3b, v72
	v_pk_fma_f32 v[66:67], v[112:113], v[66:67], v[70:71] op_sel_hi:[0,1,1]
	v_exp_f32_e32 v70, v62
	v_mul_f32_e32 v62, 0xbfb8aa3b, v73
	v_lshlrev_b32_e32 v74, 16, v63
	v_and_b32_e32 v75, 0xffff0000, v63
	v_exp_f32_e32 v71, v62
	v_mul_f32_e32 v62, 0xbfb8aa3b, v74
	v_mul_f32_e32 v63, 0xbfb8aa3b, v75
	v_exp_f32_e32 v62, v62
	v_exp_f32_e32 v63, v63
	v_pk_add_f32 v[70:71], v[70:71], 1.0 op_sel_hi:[1,0]
	v_pk_add_f32 v[62:63], v[62:63], 1.0 op_sel_hi:[1,0]
	s_nop 0
	v_rcp_f32_e32 v76, v63
	s_nop 0
	v_mul_f32_e32 v63, v75, v76
	v_rcp_f32_e32 v75, v62
	s_nop 0
	v_mul_f32_e32 v62, v74, v75
	v_pk_mul_f32 v[62:63], v[66:67], v[62:63]
	v_lshlrev_b32_e32 v67, 16, v58
	v_lshlrev_b32_e32 v66, 16, v56
	v_rcp_f32_e32 v74, v71
	s_nop 0
	v_mul_f32_e32 v71, v73, v74
	v_rcp_f32_e32 v73, v70
	s_nop 0
	v_mul_f32_e32 v70, v72, v73
	v_pk_mul_f32 v[78:79], v[68:69], v[70:71]
	v_and_b32_e32 v69, 0xffff0000, v58
	v_and_b32_e32 v68, 0xffff0000, v56
	v_lshlrev_b32_e32 v71, 16, v59
	v_lshlrev_b32_e32 v70, 16, v57
	v_and_b32_e32 v59, 0xffff0000, v59
	v_and_b32_e32 v58, 0xffff0000, v57
	v_pk_add_f32 v[56:57], v[66:67], v[68:69]
	v_pk_add_f32 v[72:73], v[70:71], v[58:59]
	s_nop 0
	v_pk_add_f32 v[56:57], v[56:57], v[72:73]
	s_nop 0
	v_add_f32_e32 v56, v56, v57
	s_nop 1
	v_add_f32_dpp v56, v56, v56 quad_perm:[1,0,3,2] row_mask:0xf bank_mask:0xf bound_ctrl:1
	s_nop 1
	v_add_f32_dpp v56, v56, v56 quad_perm:[2,3,0,1] row_mask:0xf bank_mask:0xf bound_ctrl:1
	s_nop 1
	v_add_f32_dpp v56, v56, v56 row_half_mirror row_mask:0xf bank_mask:0xf bound_ctrl:1
	v_fmac_f32_e32 v58, 0xbc800000, v56
	v_fmac_f32_e32 v68, 0xbc800000, v56
	v_fmac_f32_e32 v59, 0xbc800000, v56
	v_fmac_f32_e32 v69, 0xbc800000, v56
	v_fmac_f32_e32 v70, 0xbc800000, v56
	v_fmac_f32_e32 v66, 0xbc800000, v56
	v_fmac_f32_e32 v71, 0xbc800000, v56
	v_fmac_f32_e32 v67, 0xbc800000, v56
	v_pk_mul_f32 v[56:57], v[68:69], v[68:69]
	v_mov_b32_e32 v85, v59
	v_mov_b32_e32 v87, v58
	v_pk_mul_f32 v[58:59], v[58:59], v[58:59]
	v_pk_fma_f32 v[56:57], v[66:67], v[66:67], v[56:57]
	v_pk_fma_f32 v[58:59], v[70:71], v[70:71], v[58:59]
	v_mov_b32_e32 v80, v67
	v_pk_add_f32 v[56:57], v[56:57], v[58:59]
	v_mov_b32_e32 v81, v69
	v_add_f32_e32 v56, v56, v57
	v_mov_b32_e32 v82, v66
	v_mov_b32_e32 v83, v68
	v_add_f32_dpp v56, v56, v56 quad_perm:[1,0,3,2] row_mask:0xf bank_mask:0xf bound_ctrl:1
	v_mov_b32_e32 v84, v71
	v_mov_b32_e32 v86, v70
	v_add_f32_dpp v56, v56, v56 quad_perm:[2,3,0,1] row_mask:0xf bank_mask:0xf bound_ctrl:1
	s_nop 1
	v_add_f32_dpp v56, v56, v56 row_half_mirror row_mask:0xf bank_mask:0xf bound_ctrl:1
	v_fmamk_f32 v56, v56, 0x3c800000, v103
	v_rsq_f32_e32 v88, v56
	global_load_dwordx4 v[66:69], v[94:95], off offset:2064
	global_load_dwordx4 v[56:59], v[94:95], off offset:2048
	global_load_dwordx4 v[70:73], v[96:97], off offset:2064
	global_load_dwordx4 v[74:77], v[96:97], off offset:2048
	v_pk_mul_f32 v[82:83], v[88:89], v[82:83] op_sel_hi:[0,1]
	v_pk_mul_f32 v[86:87], v[88:89], v[86:87] op_sel_hi:[0,1]
	s_waitcnt vmcnt(0)
	v_pk_fma_f32 v[56:57], v[82:83], v[56:57], v[74:75]
	v_lshlrev_b32_e32 v74, 16, v48
	v_pk_fma_f32 v[58:59], v[86:87], v[58:59], v[76:77]
	v_and_b32_e32 v75, 0xffff0000, v48
	v_mul_f32_e32 v48, 0xbfb8aa3b, v74
	v_pk_fma_f32 v[52:53], v[110:111], v[52:53], v[58:59] op_sel_hi:[0,1,1]
	v_exp_f32_e32 v58, v48
	v_mul_f32_e32 v48, 0xbfb8aa3b, v75
	v_lshlrev_b32_e32 v76, 16, v49
	v_and_b32_e32 v77, 0xffff0000, v49
	v_exp_f32_e32 v59, v48
	v_mul_f32_e32 v48, 0xbfb8aa3b, v76
	v_mul_f32_e32 v49, 0xbfb8aa3b, v77
	v_exp_f32_e32 v48, v48
	v_exp_f32_e32 v49, v49
	v_pk_add_f32 v[58:59], v[58:59], 1.0 op_sel_hi:[1,0]
	v_pk_fma_f32 v[56:57], v[110:111], v[90:91], v[56:57] op_sel_hi:[0,1,1]
	v_pk_add_f32 v[48:49], v[48:49], 1.0 op_sel_hi:[1,0]
	s_nop 0
	v_rcp_f32_e32 v82, v49
	s_nop 0
	v_mul_f32_e32 v49, v77, v82
	v_rcp_f32_e32 v77, v48
	s_nop 0
	v_mul_f32_e32 v48, v76, v77
	v_pk_mul_f32 v[52:53], v[52:53], v[48:49]
	v_lshlrev_b32_e32 v48, 16, v54
	v_and_b32_e32 v49, 0xffff0000, v54
	v_rcp_f32_e32 v76, v59
	s_nop 0
	v_mul_f32_e32 v59, v75, v76
	v_lshlrev_b32_e32 v54, 16, v55
	v_and_b32_e32 v55, 0xffff0000, v55
	v_rcp_f32_e32 v75, v58
	s_nop 0
	v_mul_f32_e32 v58, v74, v75
	v_pk_mul_f32 v[56:57], v[56:57], v[58:59]
	v_pk_mul_f32 v[58:59], v[88:89], v[80:81] op_sel_hi:[0,1]
	v_pk_mul_f32 v[74:75], v[88:89], v[84:85] op_sel_hi:[0,1]
	v_pk_fma_f32 v[58:59], v[58:59], v[66:67], v[70:71]
	v_lshlrev_b32_e32 v66, 16, v50
	v_pk_fma_f32 v[68:69], v[74:75], v[68:69], v[72:73]
	v_and_b32_e32 v67, 0xffff0000, v50
	v_mul_f32_e32 v50, 0xbfb8aa3b, v66
	v_pk_fma_f32 v[48:49], v[110:111], v[48:49], v[58:59] op_sel_hi:[0,1,1]
	v_pk_fma_f32 v[54:55], v[110:111], v[54:55], v[68:69] op_sel_hi:[0,1,1]
	v_exp_f32_e32 v58, v50
	v_mul_f32_e32 v50, 0xbfb8aa3b, v67
	v_lshlrev_b32_e32 v68, 16, v51
	v_and_b32_e32 v69, 0xffff0000, v51
	v_exp_f32_e32 v59, v50
	v_mul_f32_e32 v50, 0xbfb8aa3b, v68
	v_mul_f32_e32 v51, 0xbfb8aa3b, v69
	v_exp_f32_e32 v50, v50
	v_exp_f32_e32 v51, v51
	v_pk_add_f32 v[58:59], v[58:59], 1.0 op_sel_hi:[1,0]
	v_pk_add_f32 v[50:51], v[50:51], 1.0 op_sel_hi:[1,0]
	s_nop 0
	v_rcp_f32_e32 v70, v51
	s_nop 0
	v_mul_f32_e32 v51, v69, v70
	v_rcp_f32_e32 v69, v50
	s_nop 0
	v_mul_f32_e32 v50, v68, v69
	v_pk_mul_f32 v[54:55], v[54:55], v[50:51]
	v_rcp_f32_e32 v68, v59
	s_nop 0
	v_mul_f32_e32 v59, v67, v68
	v_rcp_f32_e32 v67, v58
	s_nop 0
	v_mul_f32_e32 v58, v66, v67
	v_pk_mul_f32 v[58:59], v[48:49], v[58:59]
	v_cvt_pk_bf16_f32 v48, v64, v65
	v_cvt_pk_bf16_f32 v49, v60, v61
	v_add_co_u32_e32 v60, vcc, s4, v100
	v_cvt_pk_bf16_f32 v50, v78, v79
	v_cvt_pk_bf16_f32 v51, v62, v63
	v_lshlrev_b32_e32 v70, 16, v40
	s_nop 0
	v_addc_co_u32_e32 v61, vcc, 0, v101, vcc
	global_store_dwordx4 v[60:61], v[48:51], off
	v_and_b32_e32 v71, 0xffff0000, v40
	v_lshlrev_b32_e32 v40, 16, v41
	v_cvt_pk_bf16_f32 v48, v56, v57
	v_cvt_pk_bf16_f32 v49, v52, v53
	v_cvt_pk_bf16_f32 v50, v58, v59
	v_cvt_pk_bf16_f32 v51, v54, v55
	global_store_dwordx4 v[60:61], v[48:51], off offset:1024
	v_lshlrev_b32_e32 v53, 16, v47
	v_lshlrev_b32_e32 v52, 16, v45
	v_lshlrev_b32_e32 v49, 16, v46
	v_lshlrev_b32_e32 v48, 16, v44
	v_and_b32_e32 v51, 0xffff0000, v46
	v_and_b32_e32 v50, 0xffff0000, v44
	v_and_b32_e32 v47, 0xffff0000, v47
	v_and_b32_e32 v46, 0xffff0000, v45
	v_pk_add_f32 v[44:45], v[48:49], v[50:51]
	v_pk_add_f32 v[54:55], v[52:53], v[46:47]
	v_and_b32_e32 v41, 0xffff0000, v41
	v_pk_add_f32 v[44:45], v[44:45], v[54:55]
	s_nop 0
	v_add_f32_e32 v44, v44, v45
	s_nop 1
	v_add_f32_dpp v44, v44, v44 quad_perm:[1,0,3,2] row_mask:0xf bank_mask:0xf bound_ctrl:1
	s_nop 1
	v_add_f32_dpp v44, v44, v44 quad_perm:[2,3,0,1] row_mask:0xf bank_mask:0xf bound_ctrl:1
	s_nop 1
	v_add_f32_dpp v44, v44, v44 row_half_mirror row_mask:0xf bank_mask:0xf bound_ctrl:1
	v_fmac_f32_e32 v46, 0xbc800000, v44
	v_fmac_f32_e32 v50, 0xbc800000, v44
	v_fmac_f32_e32 v47, 0xbc800000, v44
	v_fmac_f32_e32 v51, 0xbc800000, v44
	v_fmac_f32_e32 v52, 0xbc800000, v44
	v_fmac_f32_e32 v48, 0xbc800000, v44
	v_fmac_f32_e32 v53, 0xbc800000, v44
	v_fmac_f32_e32 v49, 0xbc800000, v44
	v_pk_mul_f32 v[44:45], v[50:51], v[50:51]
	v_mov_b32_e32 v65, v47
	v_mov_b32_e32 v67, v46
	v_pk_mul_f32 v[46:47], v[46:47], v[46:47]
	v_pk_fma_f32 v[44:45], v[48:49], v[48:49], v[44:45]
	v_pk_fma_f32 v[46:47], v[52:53], v[52:53], v[46:47]
	v_mov_b32_e32 v60, v49
	v_pk_add_f32 v[44:45], v[44:45], v[46:47]
	v_mov_b32_e32 v61, v51
	v_add_f32_e32 v44, v44, v45
	v_mov_b32_e32 v62, v48
	v_mov_b32_e32 v63, v50
	v_add_f32_dpp v44, v44, v44 quad_perm:[1,0,3,2] row_mask:0xf bank_mask:0xf bound_ctrl:1
	v_mov_b32_e32 v64, v53
	v_mov_b32_e32 v66, v52
	v_add_f32_dpp v44, v44, v44 quad_perm:[2,3,0,1] row_mask:0xf bank_mask:0xf bound_ctrl:1
	s_nop 1
	v_add_f32_dpp v44, v44, v44 row_half_mirror row_mask:0xf bank_mask:0xf bound_ctrl:1
	v_fmamk_f32 v44, v44, 0x3c800000, v103
	v_rsq_f32_e32 v68, v44
	global_load_dwordx4 v[44:47], v[94:95], off offset:16
	global_load_dwordx4 v[48:51], v[94:95], off
	global_load_dwordx4 v[52:55], v[96:97], off offset:16
	global_load_dwordx4 v[56:59], v[96:97], off
	v_pk_mul_f32 v[62:63], v[68:69], v[62:63] op_sel_hi:[0,1]
	v_pk_mul_f32 v[66:67], v[68:69], v[66:67] op_sel_hi:[0,1]
	s_waitcnt vmcnt(0)
	v_pk_fma_f32 v[48:49], v[62:63], v[48:49], v[56:57]
	v_lshlrev_b32_e32 v56, 16, v36
	v_pk_fma_f32 v[50:51], v[66:67], v[50:51], v[58:59]
	v_and_b32_e32 v57, 0xffff0000, v36
	v_mul_f32_e32 v36, 0xbfb8aa3b, v56
	v_pk_fma_f32 v[40:41], v[108:109], v[40:41], v[50:51] op_sel_hi:[0,1,1]
	v_exp_f32_e32 v50, v36
	v_mul_f32_e32 v36, 0xbfb8aa3b, v57
	v_lshlrev_b32_e32 v58, 16, v37
	v_and_b32_e32 v59, 0xffff0000, v37
	v_exp_f32_e32 v51, v36
	v_mul_f32_e32 v36, 0xbfb8aa3b, v58
	v_mul_f32_e32 v37, 0xbfb8aa3b, v59
	v_exp_f32_e32 v36, v36
	v_exp_f32_e32 v37, v37
	v_pk_add_f32 v[50:51], v[50:51], 1.0 op_sel_hi:[1,0]
	v_pk_fma_f32 v[48:49], v[108:109], v[70:71], v[48:49] op_sel_hi:[0,1,1]
	v_pk_add_f32 v[36:37], v[36:37], 1.0 op_sel_hi:[1,0]
	s_nop 0
	v_rcp_f32_e32 v62, v37
	s_nop 0
	v_mul_f32_e32 v37, v59, v62
	v_rcp_f32_e32 v59, v36
	s_nop 0
	v_mul_f32_e32 v36, v58, v59
	v_pk_mul_f32 v[36:37], v[40:41], v[36:37]
	v_and_b32_e32 v67, 0xffff0000, v28
	v_rcp_f32_e32 v58, v51
	s_nop 0
	v_mul_f32_e32 v51, v57, v58
	v_lshlrev_b32_e32 v66, 16, v28
	v_lshlrev_b32_e32 v28, 16, v29
	v_and_b32_e32 v29, 0xffff0000, v29
	v_rcp_f32_e32 v57, v50
	s_nop 0
	v_mul_f32_e32 v50, v56, v57
	v_pk_mul_f32 v[40:41], v[48:49], v[50:51]
	v_pk_mul_f32 v[50:51], v[68:69], v[60:61] op_sel_hi:[0,1]
	v_lshlrev_b32_e32 v48, 16, v42
	v_and_b32_e32 v49, 0xffff0000, v42
	v_pk_fma_f32 v[44:45], v[50:51], v[44:45], v[52:53]
	v_pk_mul_f32 v[56:57], v[68:69], v[64:65] op_sel_hi:[0,1]
	v_pk_fma_f32 v[44:45], v[108:109], v[48:49], v[44:45] op_sel_hi:[0,1,1]
	v_lshlrev_b32_e32 v48, 16, v38
	v_lshlrev_b32_e32 v42, 16, v43
	v_and_b32_e32 v43, 0xffff0000, v43
	v_pk_fma_f32 v[46:47], v[56:57], v[46:47], v[54:55]
	v_and_b32_e32 v49, 0xffff0000, v38
	v_mul_f32_e32 v38, 0xbfb8aa3b, v48
	v_pk_fma_f32 v[42:43], v[108:109], v[42:43], v[46:47] op_sel_hi:[0,1,1]
	v_exp_f32_e32 v46, v38
	v_mul_f32_e32 v38, 0xbfb8aa3b, v49
	v_lshlrev_b32_e32 v50, 16, v39
	v_and_b32_e32 v51, 0xffff0000, v39
	v_exp_f32_e32 v47, v38
	v_mul_f32_e32 v38, 0xbfb8aa3b, v50
	v_mul_f32_e32 v39, 0xbfb8aa3b, v51
	v_exp_f32_e32 v38, v38
	v_exp_f32_e32 v39, v39
	v_pk_add_f32 v[46:47], v[46:47], 1.0 op_sel_hi:[1,0]
	v_pk_add_f32 v[38:39], v[38:39], 1.0 op_sel_hi:[1,0]
	s_nop 0
	v_rcp_f32_e32 v52, v39
	s_nop 0
	v_mul_f32_e32 v39, v51, v52
	v_rcp_f32_e32 v51, v38
	s_nop 0
	v_mul_f32_e32 v38, v50, v51
	v_pk_mul_f32 v[38:39], v[42:43], v[38:39]
	v_lshlrev_b32_e32 v43, 16, v34
	v_lshlrev_b32_e32 v42, 16, v32
	v_rcp_f32_e32 v50, v47
	s_nop 0
	v_mul_f32_e32 v47, v49, v50
	v_rcp_f32_e32 v49, v46
	s_nop 0
	v_mul_f32_e32 v46, v48, v49
	v_pk_mul_f32 v[54:55], v[44:45], v[46:47]
	v_and_b32_e32 v45, 0xffff0000, v34
	v_and_b32_e32 v44, 0xffff0000, v32
	v_lshlrev_b32_e32 v47, 16, v35
	v_lshlrev_b32_e32 v46, 16, v33
	v_and_b32_e32 v35, 0xffff0000, v35
	v_and_b32_e32 v34, 0xffff0000, v33
	v_pk_add_f32 v[32:33], v[42:43], v[44:45]
	v_pk_add_f32 v[48:49], v[46:47], v[34:35]
	s_nop 0
	v_pk_add_f32 v[32:33], v[32:33], v[48:49]
	s_nop 0
	v_add_f32_e32 v32, v32, v33
	s_nop 1
	v_add_f32_dpp v32, v32, v32 quad_perm:[1,0,3,2] row_mask:0xf bank_mask:0xf bound_ctrl:1
	s_nop 1
	v_add_f32_dpp v32, v32, v32 quad_perm:[2,3,0,1] row_mask:0xf bank_mask:0xf bound_ctrl:1
	s_nop 1
	v_add_f32_dpp v32, v32, v32 row_half_mirror row_mask:0xf bank_mask:0xf bound_ctrl:1
	v_fmac_f32_e32 v34, 0xbc800000, v32
	v_fmac_f32_e32 v44, 0xbc800000, v32
	v_fmac_f32_e32 v35, 0xbc800000, v32
	v_fmac_f32_e32 v45, 0xbc800000, v32
	v_fmac_f32_e32 v46, 0xbc800000, v32
	v_fmac_f32_e32 v42, 0xbc800000, v32
	v_fmac_f32_e32 v47, 0xbc800000, v32
	v_fmac_f32_e32 v43, 0xbc800000, v32
	v_pk_mul_f32 v[32:33], v[44:45], v[44:45]
	v_mov_b32_e32 v61, v35
	v_mov_b32_e32 v63, v34
	v_pk_mul_f32 v[34:35], v[34:35], v[34:35]
	v_pk_fma_f32 v[32:33], v[42:43], v[42:43], v[32:33]
	v_pk_fma_f32 v[34:35], v[46:47], v[46:47], v[34:35]
	v_mov_b32_e32 v56, v43
	v_pk_add_f32 v[32:33], v[32:33], v[34:35]
	v_mov_b32_e32 v57, v45
	v_add_f32_e32 v32, v32, v33
	v_mov_b32_e32 v58, v42
	v_mov_b32_e32 v59, v44
	v_add_f32_dpp v32, v32, v32 quad_perm:[1,0,3,2] row_mask:0xf bank_mask:0xf bound_ctrl:1
	v_mov_b32_e32 v60, v47
	v_mov_b32_e32 v62, v46
	v_add_f32_dpp v32, v32, v32 quad_perm:[2,3,0,1] row_mask:0xf bank_mask:0xf bound_ctrl:1
	s_nop 1
	v_add_f32_dpp v32, v32, v32 row_half_mirror row_mask:0xf bank_mask:0xf bound_ctrl:1
	v_fmamk_f32 v32, v32, 0x3c800000, v103
	v_rsq_f32_e32 v64, v32
	global_load_dwordx4 v[42:45], v[94:95], off offset:2064
	global_load_dwordx4 v[32:35], v[94:95], off offset:2048
	global_load_dwordx4 v[46:49], v[96:97], off offset:2064
	global_load_dwordx4 v[50:53], v[96:97], off offset:2048
	v_pk_mul_f32 v[58:59], v[64:65], v[58:59] op_sel_hi:[0,1]
	v_pk_mul_f32 v[62:63], v[64:65], v[62:63] op_sel_hi:[0,1]
	s_waitcnt vmcnt(0)
	v_pk_fma_f32 v[32:33], v[58:59], v[32:33], v[50:51]
	v_lshlrev_b32_e32 v50, 16, v24
	v_pk_fma_f32 v[34:35], v[62:63], v[34:35], v[52:53]
	v_and_b32_e32 v51, 0xffff0000, v24
	v_mul_f32_e32 v24, 0xbfb8aa3b, v50
	v_pk_fma_f32 v[28:29], v[106:107], v[28:29], v[34:35] op_sel_hi:[0,1,1]
	v_exp_f32_e32 v34, v24
	v_mul_f32_e32 v24, 0xbfb8aa3b, v51
	v_lshlrev_b32_e32 v52, 16, v25
	v_and_b32_e32 v53, 0xffff0000, v25
	v_exp_f32_e32 v35, v24
	v_mul_f32_e32 v24, 0xbfb8aa3b, v52
	v_mul_f32_e32 v25, 0xbfb8aa3b, v53
	v_exp_f32_e32 v24, v24
	v_exp_f32_e32 v25, v25
	v_pk_add_f32 v[34:35], v[34:35], 1.0 op_sel_hi:[1,0]
	v_pk_fma_f32 v[32:33], v[106:107], v[66:67], v[32:33] op_sel_hi:[0,1,1]
	v_pk_add_f32 v[24:25], v[24:25], 1.0 op_sel_hi:[1,0]
	s_nop 0
	v_rcp_f32_e32 v58, v25
	s_nop 0
	v_mul_f32_e32 v25, v53, v58
	v_rcp_f32_e32 v53, v24
	s_nop 0
	v_mul_f32_e32 v24, v52, v53
	v_pk_mul_f32 v[28:29], v[28:29], v[24:25]
	v_lshlrev_b32_e32 v24, 16, v30
	v_and_b32_e32 v25, 0xffff0000, v30
	v_rcp_f32_e32 v52, v35
	s_nop 0
	v_mul_f32_e32 v35, v51, v52
	v_lshlrev_b32_e32 v30, 16, v31
	v_and_b32_e32 v31, 0xffff0000, v31
	v_rcp_f32_e32 v51, v34
	s_nop 0
	v_mul_f32_e32 v34, v50, v51
	v_pk_mul_f32 v[32:33], v[32:33], v[34:35]
	v_pk_mul_f32 v[34:35], v[64:65], v[56:57] op_sel_hi:[0,1]
	v_pk_mul_f32 v[50:51], v[64:65], v[60:61] op_sel_hi:[0,1]
	v_pk_fma_f32 v[34:35], v[34:35], v[42:43], v[46:47]
	v_lshlrev_b32_e32 v42, 16, v26
	v_pk_fma_f32 v[44:45], v[50:51], v[44:45], v[48:49]
	v_and_b32_e32 v43, 0xffff0000, v26
	v_mul_f32_e32 v26, 0xbfb8aa3b, v42
	v_pk_fma_f32 v[24:25], v[106:107], v[24:25], v[34:35] op_sel_hi:[0,1,1]
	v_pk_fma_f32 v[30:31], v[106:107], v[30:31], v[44:45] op_sel_hi:[0,1,1]
	v_exp_f32_e32 v34, v26
	v_mul_f32_e32 v26, 0xbfb8aa3b, v43
	v_lshlrev_b32_e32 v44, 16, v27
	v_and_b32_e32 v45, 0xffff0000, v27
	v_exp_f32_e32 v35, v26
	v_mul_f32_e32 v26, 0xbfb8aa3b, v44
	v_mul_f32_e32 v27, 0xbfb8aa3b, v45
	v_exp_f32_e32 v26, v26
	v_exp_f32_e32 v27, v27
	v_pk_add_f32 v[34:35], v[34:35], 1.0 op_sel_hi:[1,0]
	v_pk_add_f32 v[26:27], v[26:27], 1.0 op_sel_hi:[1,0]
	s_nop 0
	v_rcp_f32_e32 v46, v27
	s_nop 0
	v_mul_f32_e32 v27, v45, v46
	v_rcp_f32_e32 v45, v26
	s_nop 0
	v_mul_f32_e32 v26, v44, v45
	v_pk_mul_f32 v[30:31], v[30:31], v[26:27]
	v_rcp_f32_e32 v44, v35
	s_nop 0
	v_mul_f32_e32 v35, v43, v44
	v_rcp_f32_e32 v43, v34
	s_nop 0
	v_mul_f32_e32 v34, v42, v43
	v_pk_mul_f32 v[34:35], v[24:25], v[34:35]
	v_cvt_pk_bf16_f32 v24, v40, v41
	v_cvt_pk_bf16_f32 v25, v36, v37
	v_add_co_u32_e32 v36, vcc, s5, v100
	v_cvt_pk_bf16_f32 v26, v54, v55
	v_cvt_pk_bf16_f32 v27, v38, v39
	v_lshlrev_b32_e32 v46, 16, v16
	s_nop 0
	v_addc_co_u32_e32 v37, vcc, 0, v101, vcc
	global_store_dwordx4 v[36:37], v[24:27], off
	v_and_b32_e32 v47, 0xffff0000, v16
	v_lshlrev_b32_e32 v16, 16, v17
	v_cvt_pk_bf16_f32 v24, v32, v33
	v_cvt_pk_bf16_f32 v25, v28, v29
	v_cvt_pk_bf16_f32 v26, v34, v35
	v_cvt_pk_bf16_f32 v27, v30, v31
	global_store_dwordx4 v[36:37], v[24:27], off offset:1024
	v_lshlrev_b32_e32 v29, 16, v23
	v_lshlrev_b32_e32 v28, 16, v21
	v_lshlrev_b32_e32 v25, 16, v22
	v_lshlrev_b32_e32 v24, 16, v20
	v_and_b32_e32 v27, 0xffff0000, v22
	v_and_b32_e32 v26, 0xffff0000, v20
	v_and_b32_e32 v23, 0xffff0000, v23
	v_and_b32_e32 v22, 0xffff0000, v21
	v_pk_add_f32 v[20:21], v[24:25], v[26:27]
	v_pk_add_f32 v[30:31], v[28:29], v[22:23]
	v_and_b32_e32 v17, 0xffff0000, v17
	v_pk_add_f32 v[20:21], v[20:21], v[30:31]
	s_nop 0
	v_add_f32_e32 v20, v20, v21
	s_nop 1
	v_add_f32_dpp v20, v20, v20 quad_perm:[1,0,3,2] row_mask:0xf bank_mask:0xf bound_ctrl:1
	s_nop 1
	v_add_f32_dpp v20, v20, v20 quad_perm:[2,3,0,1] row_mask:0xf bank_mask:0xf bound_ctrl:1
	s_nop 1
	v_add_f32_dpp v20, v20, v20 row_half_mirror row_mask:0xf bank_mask:0xf bound_ctrl:1
	v_fmac_f32_e32 v22, 0xbc800000, v20
	v_fmac_f32_e32 v26, 0xbc800000, v20
	v_fmac_f32_e32 v23, 0xbc800000, v20
	v_fmac_f32_e32 v27, 0xbc800000, v20
	v_fmac_f32_e32 v28, 0xbc800000, v20
	v_fmac_f32_e32 v24, 0xbc800000, v20
	v_fmac_f32_e32 v29, 0xbc800000, v20
	v_fmac_f32_e32 v25, 0xbc800000, v20
	v_pk_mul_f32 v[20:21], v[26:27], v[26:27]
	v_mov_b32_e32 v41, v23
	v_mov_b32_e32 v43, v22
	v_pk_mul_f32 v[22:23], v[22:23], v[22:23]
	v_pk_fma_f32 v[20:21], v[24:25], v[24:25], v[20:21]
	v_pk_fma_f32 v[22:23], v[28:29], v[28:29], v[22:23]
	v_mov_b32_e32 v36, v25
	v_pk_add_f32 v[20:21], v[20:21], v[22:23]
	v_mov_b32_e32 v37, v27
	v_add_f32_e32 v20, v20, v21
	v_mov_b32_e32 v38, v24
	v_mov_b32_e32 v39, v26
	v_add_f32_dpp v20, v20, v20 quad_perm:[1,0,3,2] row_mask:0xf bank_mask:0xf bound_ctrl:1
	v_mov_b32_e32 v40, v29
	v_mov_b32_e32 v42, v28
	v_add_f32_dpp v20, v20, v20 quad_perm:[2,3,0,1] row_mask:0xf bank_mask:0xf bound_ctrl:1
	s_nop 1
	v_add_f32_dpp v20, v20, v20 row_half_mirror row_mask:0xf bank_mask:0xf bound_ctrl:1
	v_fmamk_f32 v20, v20, 0x3c800000, v103
	v_rsq_f32_e32 v44, v20
	global_load_dwordx4 v[20:23], v[94:95], off offset:16
	global_load_dwordx4 v[24:27], v[94:95], off
	global_load_dwordx4 v[28:31], v[96:97], off offset:16
	global_load_dwordx4 v[32:35], v[96:97], off
	v_pk_mul_f32 v[38:39], v[44:45], v[38:39] op_sel_hi:[0,1]
	v_pk_mul_f32 v[42:43], v[44:45], v[42:43] op_sel_hi:[0,1]
	s_waitcnt vmcnt(0)
	v_pk_fma_f32 v[24:25], v[38:39], v[24:25], v[32:33]
	v_lshlrev_b32_e32 v32, 16, v12
	v_pk_fma_f32 v[26:27], v[42:43], v[26:27], v[34:35]
	v_and_b32_e32 v33, 0xffff0000, v12
	v_mul_f32_e32 v12, 0xbfb8aa3b, v32
	v_pk_fma_f32 v[16:17], v[104:105], v[16:17], v[26:27] op_sel_hi:[0,1,1]
	v_exp_f32_e32 v26, v12
	v_mul_f32_e32 v12, 0xbfb8aa3b, v33
	v_lshlrev_b32_e32 v34, 16, v13
	v_and_b32_e32 v35, 0xffff0000, v13
	v_exp_f32_e32 v27, v12
	v_mul_f32_e32 v12, 0xbfb8aa3b, v34
	v_mul_f32_e32 v13, 0xbfb8aa3b, v35
	v_exp_f32_e32 v12, v12
	v_exp_f32_e32 v13, v13
	v_pk_add_f32 v[26:27], v[26:27], 1.0 op_sel_hi:[1,0]
	v_pk_fma_f32 v[24:25], v[104:105], v[46:47], v[24:25] op_sel_hi:[0,1,1]
	v_pk_add_f32 v[12:13], v[12:13], 1.0 op_sel_hi:[1,0]
	s_nop 0
	v_rcp_f32_e32 v38, v13
	s_nop 0
	v_mul_f32_e32 v13, v35, v38
	v_rcp_f32_e32 v35, v12
	s_nop 0
	v_mul_f32_e32 v12, v34, v35
	v_pk_mul_f32 v[12:13], v[16:17], v[12:13]
	v_and_b32_e32 v43, 0xffff0000, v4
	v_rcp_f32_e32 v34, v27
	s_nop 0
	v_mul_f32_e32 v27, v33, v34
	v_lshlrev_b32_e32 v42, 16, v4
	v_lshlrev_b32_e32 v4, 16, v5
	v_and_b32_e32 v5, 0xffff0000, v5
	v_rcp_f32_e32 v33, v26
	s_nop 0
	v_mul_f32_e32 v26, v32, v33
	v_pk_mul_f32 v[16:17], v[24:25], v[26:27]
	v_pk_mul_f32 v[26:27], v[44:45], v[36:37] op_sel_hi:[0,1]
	v_lshlrev_b32_e32 v24, 16, v18
	v_and_b32_e32 v25, 0xffff0000, v18
	v_pk_fma_f32 v[20:21], v[26:27], v[20:21], v[28:29]
	v_pk_mul_f32 v[32:33], v[44:45], v[40:41] op_sel_hi:[0,1]
	v_pk_fma_f32 v[20:21], v[104:105], v[24:25], v[20:21] op_sel_hi:[0,1,1]
	v_lshlrev_b32_e32 v24, 16, v14
	v_lshlrev_b32_e32 v18, 16, v19
	v_and_b32_e32 v19, 0xffff0000, v19
	v_pk_fma_f32 v[22:23], v[32:33], v[22:23], v[30:31]
	v_and_b32_e32 v25, 0xffff0000, v14
	v_mul_f32_e32 v14, 0xbfb8aa3b, v24
	v_pk_fma_f32 v[18:19], v[104:105], v[18:19], v[22:23] op_sel_hi:[0,1,1]
	v_exp_f32_e32 v22, v14
	v_mul_f32_e32 v14, 0xbfb8aa3b, v25
	v_lshlrev_b32_e32 v26, 16, v15
	v_and_b32_e32 v27, 0xffff0000, v15
	v_exp_f32_e32 v23, v14
	v_mul_f32_e32 v14, 0xbfb8aa3b, v26
	v_mul_f32_e32 v15, 0xbfb8aa3b, v27
	v_exp_f32_e32 v14, v14
	v_exp_f32_e32 v15, v15
	v_pk_add_f32 v[22:23], v[22:23], 1.0 op_sel_hi:[1,0]
	v_pk_add_f32 v[14:15], v[14:15], 1.0 op_sel_hi:[1,0]
	s_nop 0
	v_rcp_f32_e32 v28, v15
	s_nop 0
	v_mul_f32_e32 v15, v27, v28
	v_rcp_f32_e32 v27, v14
	s_nop 0
	v_mul_f32_e32 v14, v26, v27
	v_pk_mul_f32 v[14:15], v[18:19], v[14:15]
	v_lshlrev_b32_e32 v19, 16, v10
	v_lshlrev_b32_e32 v18, 16, v8
	v_rcp_f32_e32 v26, v23
	s_nop 0
	v_mul_f32_e32 v23, v25, v26
	v_rcp_f32_e32 v25, v22
	s_nop 0
	v_mul_f32_e32 v22, v24, v25
	v_pk_mul_f32 v[30:31], v[20:21], v[22:23]
	v_and_b32_e32 v21, 0xffff0000, v10
	v_and_b32_e32 v20, 0xffff0000, v8
	v_lshlrev_b32_e32 v23, 16, v11
	v_lshlrev_b32_e32 v22, 16, v9
	v_and_b32_e32 v11, 0xffff0000, v11
	v_and_b32_e32 v10, 0xffff0000, v9
	v_pk_add_f32 v[8:9], v[18:19], v[20:21]
	v_pk_add_f32 v[24:25], v[22:23], v[10:11]
	s_nop 0
	v_pk_add_f32 v[8:9], v[8:9], v[24:25]
	s_nop 0
	v_add_f32_e32 v8, v8, v9
	s_nop 1
	v_add_f32_dpp v8, v8, v8 quad_perm:[1,0,3,2] row_mask:0xf bank_mask:0xf bound_ctrl:1
	s_nop 1
	v_add_f32_dpp v8, v8, v8 quad_perm:[2,3,0,1] row_mask:0xf bank_mask:0xf bound_ctrl:1
	s_nop 1
	v_add_f32_dpp v8, v8, v8 row_half_mirror row_mask:0xf bank_mask:0xf bound_ctrl:1
	v_fmac_f32_e32 v10, 0xbc800000, v8
	v_fmac_f32_e32 v20, 0xbc800000, v8
	v_fmac_f32_e32 v11, 0xbc800000, v8
	v_fmac_f32_e32 v21, 0xbc800000, v8
	v_fmac_f32_e32 v22, 0xbc800000, v8
	v_fmac_f32_e32 v18, 0xbc800000, v8
	v_fmac_f32_e32 v23, 0xbc800000, v8
	v_fmac_f32_e32 v19, 0xbc800000, v8
	v_pk_mul_f32 v[8:9], v[20:21], v[20:21]
	v_mov_b32_e32 v37, v11
	v_mov_b32_e32 v39, v10
	v_pk_mul_f32 v[10:11], v[10:11], v[10:11]
	v_pk_fma_f32 v[8:9], v[18:19], v[18:19], v[8:9]
	v_pk_fma_f32 v[10:11], v[22:23], v[22:23], v[10:11]
	v_mov_b32_e32 v32, v19
	v_pk_add_f32 v[8:9], v[8:9], v[10:11]
	v_mov_b32_e32 v33, v21
	v_add_f32_e32 v8, v8, v9
	v_mov_b32_e32 v34, v18
	v_mov_b32_e32 v35, v20
	v_add_f32_dpp v8, v8, v8 quad_perm:[1,0,3,2] row_mask:0xf bank_mask:0xf bound_ctrl:1
	v_mov_b32_e32 v36, v23
	v_mov_b32_e32 v38, v22
	v_add_f32_dpp v8, v8, v8 quad_perm:[2,3,0,1] row_mask:0xf bank_mask:0xf bound_ctrl:1
	s_nop 1
	v_add_f32_dpp v8, v8, v8 row_half_mirror row_mask:0xf bank_mask:0xf bound_ctrl:1
	v_fmamk_f32 v8, v8, 0x3c800000, v103
	v_rsq_f32_e32 v40, v8
	global_load_dwordx4 v[18:21], v[94:95], off offset:2064
	global_load_dwordx4 v[8:11], v[94:95], off offset:2048
	global_load_dwordx4 v[22:25], v[96:97], off offset:2064
	global_load_dwordx4 v[26:29], v[96:97], off offset:2048
	v_pk_mul_f32 v[34:35], v[40:41], v[34:35] op_sel_hi:[0,1]
	v_pk_mul_f32 v[38:39], v[40:41], v[38:39] op_sel_hi:[0,1]
	s_waitcnt vmcnt(0)
	v_pk_fma_f32 v[8:9], v[34:35], v[8:9], v[26:27]
	v_lshlrev_b32_e32 v26, 16, v0
	v_pk_fma_f32 v[10:11], v[38:39], v[10:11], v[28:29]
	v_and_b32_e32 v27, 0xffff0000, v0
	v_mul_f32_e32 v0, 0xbfb8aa3b, v26
	v_pk_fma_f32 v[4:5], v[102:103], v[4:5], v[10:11] op_sel_hi:[0,1,1]
	v_exp_f32_e32 v10, v0
	v_mul_f32_e32 v0, 0xbfb8aa3b, v27
	v_lshlrev_b32_e32 v28, 16, v1
	v_and_b32_e32 v29, 0xffff0000, v1
	v_exp_f32_e32 v11, v0
	v_mul_f32_e32 v0, 0xbfb8aa3b, v28
	v_mul_f32_e32 v1, 0xbfb8aa3b, v29
	v_exp_f32_e32 v0, v0
	v_exp_f32_e32 v1, v1
	v_pk_add_f32 v[10:11], v[10:11], 1.0 op_sel_hi:[1,0]
	v_pk_fma_f32 v[8:9], v[102:103], v[42:43], v[8:9] op_sel_hi:[0,1,1]
	v_pk_add_f32 v[0:1], v[0:1], 1.0 op_sel_hi:[1,0]
	s_nop 0
	v_rcp_f32_e32 v34, v1
	s_nop 0
	v_mul_f32_e32 v1, v29, v34
	v_rcp_f32_e32 v29, v0
	s_nop 0
	v_mul_f32_e32 v0, v28, v29
	v_pk_mul_f32 v[4:5], v[4:5], v[0:1]
	v_lshlrev_b32_e32 v0, 16, v6
	v_and_b32_e32 v1, 0xffff0000, v6
	v_rcp_f32_e32 v28, v11
	s_nop 0
	v_mul_f32_e32 v11, v27, v28
	v_lshlrev_b32_e32 v6, 16, v7
	v_and_b32_e32 v7, 0xffff0000, v7
	v_rcp_f32_e32 v27, v10
	s_nop 0
	v_mul_f32_e32 v10, v26, v27
	v_pk_mul_f32 v[8:9], v[8:9], v[10:11]
	v_pk_mul_f32 v[10:11], v[40:41], v[32:33] op_sel_hi:[0,1]
	v_pk_mul_f32 v[26:27], v[40:41], v[36:37] op_sel_hi:[0,1]
	v_pk_fma_f32 v[10:11], v[10:11], v[18:19], v[22:23]
	v_lshlrev_b32_e32 v18, 16, v2
	v_pk_fma_f32 v[20:21], v[26:27], v[20:21], v[24:25]
	v_and_b32_e32 v19, 0xffff0000, v2
	v_mul_f32_e32 v2, 0xbfb8aa3b, v18
	v_pk_fma_f32 v[0:1], v[102:103], v[0:1], v[10:11] op_sel_hi:[0,1,1]
	v_pk_fma_f32 v[6:7], v[102:103], v[6:7], v[20:21] op_sel_hi:[0,1,1]
	v_exp_f32_e32 v10, v2
	v_mul_f32_e32 v2, 0xbfb8aa3b, v19
	v_lshlrev_b32_e32 v20, 16, v3
	v_and_b32_e32 v21, 0xffff0000, v3
	v_exp_f32_e32 v11, v2
	v_mul_f32_e32 v2, 0xbfb8aa3b, v20
	v_mul_f32_e32 v3, 0xbfb8aa3b, v21
	v_exp_f32_e32 v2, v2
	v_exp_f32_e32 v3, v3
	v_pk_add_f32 v[10:11], v[10:11], 1.0 op_sel_hi:[1,0]
	v_pk_add_f32 v[2:3], v[2:3], 1.0 op_sel_hi:[1,0]
	s_nop 0
	v_rcp_f32_e32 v22, v3
	s_nop 0
	v_mul_f32_e32 v3, v21, v22
	v_rcp_f32_e32 v21, v2
	s_nop 0
	v_mul_f32_e32 v2, v20, v21
	v_pk_mul_f32 v[6:7], v[6:7], v[2:3]
	v_rcp_f32_e32 v20, v11
	s_nop 0
	v_mul_f32_e32 v11, v19, v20
	v_rcp_f32_e32 v19, v10
	s_nop 0
	v_mul_f32_e32 v10, v18, v19
	v_pk_mul_f32 v[10:11], v[0:1], v[10:11]
	v_cvt_pk_bf16_f32 v0, v16, v17
	v_cvt_pk_bf16_f32 v1, v12, v13
	v_add_co_u32_e32 v12, vcc, s12, v100
	v_cvt_pk_bf16_f32 v2, v30, v31
	v_cvt_pk_bf16_f32 v3, v14, v15
	s_nop 1
	v_addc_co_u32_e32 v13, vcc, 0, v101, vcc
	global_store_dwordx4 v[12:13], v[0:3], off
	s_nop 1
	v_cvt_pk_bf16_f32 v0, v8, v9
	v_cvt_pk_bf16_f32 v1, v4, v5
	v_cvt_pk_bf16_f32 v2, v10, v11
	v_cvt_pk_bf16_f32 v3, v6, v7
	global_store_dwordx4 v[12:13], v[0:3], off offset:1024
	s_cbranch_scc0 .LBB0_904
